# NSA selected loop unrolled by two: LDS buffer parity moved into ds_read immediate offsets, 12 per-step v_xor address toggles removed
# speedup vs baseline: 1.0045x; 1.0022x over previous
; DI void st_reset(AttnSt& st) {
; #pragma unroll
;   for (int h = 0; h < 2; ++h) {
;     st.m[h] = -1e30f;
;     st.l[h] = 0.f;
;     st.L[h] = f32x4{0.f, 0.f, 0.f, 0.f};
; #pragma unroll
;     for (int dt = 0; dt < 4; ++dt) st.O[h][dt] = f32x4{0.f, 0.f, 0.f, 0.f};
;   }
; }
; template <bool FX>
; DI void nsa_tile(const Params& p, int b, int g, int tile, bf16_t* lds, const float CL) {
;     ...
;   for (int hp = 0; hp < 2; ++hp) {
; #pragma unroll
;     for (int hh = 0; hh < 2; ++hh)
; #pragma unroll
;       for (int ks = 0; ks < 2; ++ks) qf[hh][ks] = *(const bf16x8*)(ztok + C_Q + g * 256 + (hp * 2 + hh) * 64 + ks * 32 + quad * 8);
;     st_reset(st);
;     {
;       const bf16_t* kb = zb + C_KS + g * 64;
;       tile64_gload(tid, rk0, rk1, kb, ZS);
;       tile64_gload(tid, rv0, rv1, vsT, TS);
;       for (int s = 0; s <= cur; ++s) {
;         __syncthreads();
;         tile64_sstore(tid, Ks, rk0, rk1);
;         tile64_sstore(tid, Vs, rv0, rv1);
;         __syncthreads();
;         if (s < cur) {
;           tile64_gload(tid, rk0, rk1, kb + (size_t)(s + 1) * 64 * ZS, ZS);
;           tile64_gload(tid, rv0, rv1, vsT + (s + 1) * 64, TS);
.LBB0_665:
	s_lshl_b32 s28, s6, 8
	v_lshl_add_u64 v[14:15], v[116:117], 0, s[28:29]
	global_load_dwordx4 v[2:5], v[14:15], off
	global_load_dwordx4 v[6:9], v[14:15], off offset:64
	global_load_dwordx4 v[10:13], v[14:15], off offset:128
	s_nop 0
	global_load_dwordx4 v[14:17], v[14:15], off offset:192
	s_nop 0
	v_and_b32_e32 v202, 7, v196
	v_bfe_u32 v218, v196, 4, 3
	v_xor_b32_e32 v202, v202, v218
	v_lshlrev_b32_e32 v202, 4, v202
	v_mov_b32_e32 v203, 0
	v_sub_u32_e32 v218, v202, v0
	v_ashrrev_i32_e32 v219, 31, v218
	v_readfirstlane_b32 s77, v196
	s_lshr_b32 s76, s77, 8
	s_lshl_b32 s76, s76, 16
	s_bfe_u32 s77, s77, 0x20006
	s_lshl_b32 s77, s77, 10
	s_or_b32 s76, s76, s77
	s_or_b32 s76, s76, 0xc000
	s_movk_i32 s78, 0x600
	s_mov_b32 s79, 0
	v_lshl_add_u64 v[58:59], v[132:133], 0, v[218:219]
	v_lshl_add_u64 v[60:61], v[136:137], 0, v[218:219]
	v_lshl_add_u64 v[62:63], v[140:141], 0, v[218:219]
	v_lshl_add_u64 v[64:65], v[144:145], 0, v[218:219]
	v_lshl_add_u64 v[58:59], v[58:59], 0, s[78:79]
	v_lshl_add_u64 v[60:61], v[60:61], 0, s[78:79]
	s_mov_b32 m0, s76
	s_nop 0
	global_load_lds_dwordx4 v[58:59], off
	s_add_u32 m0, s76, 0x1000
	s_nop 0
	global_load_lds_dwordx4 v[60:61], off
	s_add_u32 m0, s76, 0x2000
	s_nop 0
	global_load_lds_dwordx4 v[62:63], off
	s_add_u32 m0, s76, 0x3000
	s_nop 0
	global_load_lds_dwordx4 v[64:65], off
	s_xor_b32 s76, s76, 0xc000
	v_mov_b32_e32 v54, v1
	v_mov_b32_e32 v55, v1
	v_mov_b32_e32 v56, v1
	v_mov_b32_e32 v57, v1
	v_mov_b64_e32 v[46:47], v[54:55]
	v_mov_b64_e32 v[50:51], v[54:55]
	v_mov_b64_e32 v[42:43], v[54:55]
	v_mov_b64_e32 v[38:39], v[54:55]
	v_mov_b64_e32 v[34:35], v[54:55]
	v_mov_b64_e32 v[30:31], v[54:55]
	v_mov_b64_e32 v[26:27], v[54:55]
	v_mov_b64_e32 v[22:23], v[54:55]
	v_mov_b64_e32 v[18:19], v[54:55]
	s_xor_b64 s[36:37], s[2:3], -1
	s_lshl_b32 s7, s6, 7
	s_mov_b32 s28, 64
	s_mov_b32 s68, -1
	v_mov_b32_e32 v187, v185
	v_lshl_add_u64 v[158:159], v[156:157], 0, v[218:219]
	v_lshl_add_u64 v[160:161], v[154:155], 0, v[218:219]
	v_mov_b64_e32 v[48:49], v[56:57]
	v_mov_b64_e32 v[52:53], v[56:57]
	v_mov_b64_e32 v[44:45], v[56:57]
	v_mov_b64_e32 v[40:41], v[56:57]
	v_mov_b64_e32 v[36:37], v[56:57]
	v_mov_b64_e32 v[32:33], v[56:57]
	v_mov_b64_e32 v[28:29], v[56:57]
	v_mov_b64_e32 v[24:25], v[56:57]
	v_mov_b64_e32 v[20:21], v[56:57]
	s_branch .LBB0_668_p1
; template <int MODE, bool FX>
; DI void attn_compute(const int lane, const bf16_t* Ks, const bf16_t* Vs, const bf16x8 (&qf)[2][2], AttnSt& st, const float (&invl)[2],
;                      int lo, int hi, float (&impA)[4], float (&impE)[4], const float CL) {
;     ...
;   if (__all(full || none)) {
;     constexpr float L2E = 1.4426950408889634f;
; #pragma unroll
;     for (int hh = 0; hh < 2; ++hh) {
;       float mL;
;       float il = 1.f;
;       if (FX) {
;         mL = full ? CL : 1e30f;
;         if (MODE == 1) il = invl[hh];
;       } else if (MODE != 1) {
;         float mx = -1e30f;
; #pragma unroll
;         for (int kt = 0; kt < 4; ++kt)
; #pragma unroll
;           for (int j = 0; j < 4; ++j) mx = fmaxf(mx, S[kt][hh][j]);
;         mx = full ? mx : -1e30f;
;         mx = fmaxf(mx, shx(mx, 16, lane));
;         mx = fmaxf(mx, shx(mx, 32, lane));
;         const float m_new = fmaxf(st.m[hh], mx);
;         const float alpha = __expf(st.m[hh] - m_new);
;         st.m[hh] = m_new;
;         st.l[hh] *= alpha;
;         if (MODE == 2) {
; #pragma unroll
;           for (int dt = 0; dt < 4; ++dt) st.O[hh][dt] *= alpha;
;         }
;         mL = full ? m_new * L2E : 1e30f;
;       } else {
;         mL = full ? st.m[hh] * L2E : 1e30f;
;         il = invl[hh];
;       }
;       float rs = 0.f;
; #pragma unroll
;       for (int kt = 0; kt < 4; ++kt) {
;         float a = 0.f;
; #pragma unroll
;         for (int j = 0; j < 4; ++j) {
;           float pv = __builtin_amdgcn_exp2f(fmaf(S[kt][hh][j], L2E, -mL));
;           if (MODE == 1) pv *= il;
;           S[kt][hh][j] = pv;
;           a += pv;
;         }
;         rs += a;
;         if (MODE == 1) {
;           impA[kt] += a;
;           impE[kt] += S[kt][hh][3];
;         }
;       }
;       if (MODE != 1 && !(FX && MODE == 2)) st.l[hh] += rs;
;       if (MODE != 0) {
; #pragma unroll
;         for (int c = 0; c < 2; ++c)
;           pf[hh][c] = mk8(pack2(S[2 * c][hh][0], S[2 * c][hh][1]), pack2(S[2 * c][hh][2], S[2 * c][hh][3]),
;                           pack2(S[2 * c + 1][hh][0], S[2 * c + 1][hh][1]), pack2(S[2 * c + 1][hh][2], S[2 * c + 1][hh][3]));
;       }
;     }
;     ...
;   if (MODE != 0) {
; #pragma unroll
;     for (int dt = 0; dt < 4; ++dt) {
;       const int row = dt * 16 + col;
;       const int sw = (row >> 1) & 7;
; #pragma unroll
;       for (int c = 0; c < 2; ++c) {
.Lnsa_fast_p1:
	s_waitcnt lgkmcnt(7)
	v_mfma_f32_16x16x32_bf16 v[98:101], v[220:223], v[2:5], 0
	s_waitcnt lgkmcnt(6)
	v_mfma_f32_16x16x32_bf16 v[106:109], v[224:227], v[2:5], 0
	s_waitcnt lgkmcnt(5)
	v_mfma_f32_16x16x32_bf16 v[102:105], v[228:231], v[2:5], 0
	s_waitcnt lgkmcnt(4)
	v_mfma_f32_16x16x32_bf16 v[110:113], v[232:235], v[2:5], 0
	s_waitcnt lgkmcnt(3)
	v_mfma_f32_16x16x32_bf16 v[98:101], v[236:239], v[6:9], v[98:101]
	s_waitcnt lgkmcnt(2)
	v_mfma_f32_16x16x32_bf16 v[106:109], v[240:243], v[6:9], v[106:109]
	s_waitcnt lgkmcnt(1)
	v_mfma_f32_16x16x32_bf16 v[102:105], v[244:247], v[6:9], v[102:105]
	s_waitcnt lgkmcnt(0)
	v_mfma_f32_16x16x32_bf16 v[110:113], v[198:201], v[6:9], v[110:113]
	v_cmp_lt_i32_e32 vcc, 62, v215
	v_mfma_f32_16x16x32_bf16 v[90:93], v[220:223], v[10:13], 0
	v_mfma_f32_16x16x32_bf16 v[94:97], v[224:227], v[10:13], 0
	v_cndmask_b32_e32 v217, v197, v205, vcc
	v_mfma_f32_16x16x32_bf16 v[82:85], v[228:231], v[10:13], 0
	v_mfma_f32_16x16x32_bf16 v[86:89], v[232:235], v[10:13], 0
	v_fmamk_f32 v74, v98, 0x3fb8aa3b, v217
	v_fmamk_f32 v75, v99, 0x3fb8aa3b, v217
	v_mfma_f32_16x16x32_bf16 v[90:93], v[236:239], v[14:17], v[90:93]
	v_fmamk_f32 v76, v100, 0x3fb8aa3b, v217
	v_fmamk_f32 v77, v101, 0x3fb8aa3b, v217
	v_mfma_f32_16x16x32_bf16 v[94:97], v[240:243], v[14:17], v[94:97]
	v_fmamk_f32 v78, v106, 0x3fb8aa3b, v217
	v_fmamk_f32 v79, v107, 0x3fb8aa3b, v217
	v_mfma_f32_16x16x32_bf16 v[82:85], v[244:247], v[14:17], v[82:85]
	v_fmamk_f32 v80, v108, 0x3fb8aa3b, v217
	v_fmamk_f32 v81, v109, 0x3fb8aa3b, v217
	v_mfma_f32_16x16x32_bf16 v[86:89], v[198:201], v[14:17], v[86:89]
	ds_read_b64 v[220:221], v207 offset:57344
	v_fmamk_f32 v164, v102, 0x3fb8aa3b, v217
	ds_read_b64 v[222:223], v208 offset:57344
	v_fmamk_f32 v165, v103, 0x3fb8aa3b, v217
	ds_read_b64 v[224:225], v209 offset:57344
	v_fmamk_f32 v166, v104, 0x3fb8aa3b, v217
	ds_read_b64 v[226:227], v210 offset:57344
	v_fmamk_f32 v167, v105, 0x3fb8aa3b, v217
	ds_read_b64 v[228:229], v207 offset:59392
	v_fmamk_f32 v168, v110, 0x3fb8aa3b, v217
	ds_read_b64 v[230:231], v208 offset:59392
	v_fmamk_f32 v169, v111, 0x3fb8aa3b, v217
	ds_read_b64 v[232:233], v209 offset:59392
	v_fmamk_f32 v170, v112, 0x3fb8aa3b, v217
	ds_read_b64 v[234:235], v210 offset:59392
	v_fmamk_f32 v171, v113, 0x3fb8aa3b, v217
	ds_read_b64 v[236:237], v207 offset:61440
	v_exp_f32_e32 v74, v74
	ds_read_b64 v[238:239], v208 offset:61440
	v_exp_f32_e32 v75, v75
	ds_read_b64 v[240:241], v209 offset:61440
	v_exp_f32_e32 v76, v76
	ds_read_b64 v[242:243], v210 offset:61440
	v_exp_f32_e32 v77, v77
	ds_read_b64 v[244:245], v211 offset:57344
	v_exp_f32_e32 v78, v78
	ds_read_b64 v[246:247], v212 offset:57344
	v_exp_f32_e32 v79, v79
	ds_read_b64 v[198:199], v213 offset:57344
	v_exp_f32_e32 v80, v80
	ds_read_b64 v[200:201], v214 offset:57344
	v_exp_f32_e32 v81, v81
	v_exp_f32_e32 v164, v164
	v_exp_f32_e32 v165, v165
	v_exp_f32_e32 v166, v166
	v_exp_f32_e32 v167, v167
	v_exp_f32_e32 v168, v168
	v_exp_f32_e32 v169, v169
	v_exp_f32_e32 v170, v170
	v_exp_f32_e32 v171, v171
	v_cvt_pk_bf16_f32 v74, v74, v75
	v_cvt_pk_bf16_f32 v75, v76, v77
	v_cvt_pk_bf16_f32 v76, v78, v79
	v_cvt_pk_bf16_f32 v77, v80, v81
	v_cvt_pk_bf16_f32 v78, v164, v165
	v_cvt_pk_bf16_f32 v79, v166, v167
	v_cvt_pk_bf16_f32 v80, v168, v169
	v_cvt_pk_bf16_f32 v81, v170, v171
	s_waitcnt lgkmcnt(0)
	v_fmamk_f32 v164, v90, 0x3fb8aa3b, v217
	v_fmamk_f32 v165, v91, 0x3fb8aa3b, v217
	v_fmamk_f32 v166, v92, 0x3fb8aa3b, v217
	v_mfma_f32_16x16x32_bf16 v[50:53], v[220:223], v[74:77], v[50:53]
	v_fmamk_f32 v167, v93, 0x3fb8aa3b, v217
	s_mov_b32 s10, s8
	s_mov_b32 s11, s8
	s_mov_b32 s9, s8
	v_mfma_f32_16x16x32_bf16 v[42:45], v[228:231], v[74:77], v[42:45]
	v_mov_b64_e32 v[92:93], s[10:11]
	v_mov_b64_e32 v[90:91], s[8:9]
	v_fmamk_f32 v168, v94, 0x3fb8aa3b, v217
	v_fmamk_f32 v169, v95, 0x3fb8aa3b, v217
	v_mfma_f32_16x16x32_bf16 v[38:41], v[236:239], v[74:77], v[38:41]
	v_fmamk_f32 v170, v96, 0x3fb8aa3b, v217
	v_fmamk_f32 v171, v97, 0x3fb8aa3b, v217
	v_fmamk_f32 v172, v82, 0x3fb8aa3b, v217
	v_fmamk_f32 v173, v83, 0x3fb8aa3b, v217
	v_mfma_f32_16x16x32_bf16 v[34:37], v[244:247], v[74:77], v[34:37]
	v_fmamk_f32 v174, v84, 0x3fb8aa3b, v217
	v_fmamk_f32 v175, v85, 0x3fb8aa3b, v217
	v_fmamk_f32 v176, v86, 0x3fb8aa3b, v217
	v_fmamk_f32 v177, v87, 0x3fb8aa3b, v217
	v_mfma_f32_16x16x32_bf16 v[50:53], v[224:227], v[78:81], v[50:53]
	v_fmamk_f32 v178, v88, 0x3fb8aa3b, v217
	v_fmamk_f32 v179, v89, 0x3fb8aa3b, v217
	v_exp_f32_e32 v164, v164
	v_exp_f32_e32 v165, v165
	v_mfma_f32_16x16x32_bf16 v[42:45], v[232:235], v[78:81], v[42:45]
	v_exp_f32_e32 v166, v166
	v_exp_f32_e32 v167, v167
	v_exp_f32_e32 v168, v168
	v_exp_f32_e32 v169, v169
	v_mfma_f32_16x16x32_bf16 v[38:41], v[240:243], v[78:81], v[38:41]
	v_exp_f32_e32 v170, v170
	v_exp_f32_e32 v171, v171
	v_exp_f32_e32 v172, v172
	v_exp_f32_e32 v173, v173
	v_mfma_f32_16x16x32_bf16 v[34:37], v[198:201], v[78:81], v[34:37]
	v_exp_f32_e32 v174, v174
	v_exp_f32_e32 v175, v175
	v_exp_f32_e32 v176, v176
	v_exp_f32_e32 v177, v177
	v_mfma_f32_16x16x32_bf16 v[54:57], v[90:93], v[74:77], v[54:57]
	v_exp_f32_e32 v178, v178
	v_exp_f32_e32 v179, v179
	v_cvt_pk_bf16_f32 v82, v164, v165
	v_cvt_pk_bf16_f32 v83, v166, v167
	v_mfma_f32_16x16x32_bf16 v[54:57], v[90:93], v[78:81], v[54:57]
	v_cvt_pk_bf16_f32 v84, v168, v169
	v_cvt_pk_bf16_f32 v85, v170, v171
	v_cvt_pk_bf16_f32 v86, v172, v173
	v_cvt_pk_bf16_f32 v87, v174, v175
	v_cvt_pk_bf16_f32 v88, v176, v177
	v_cvt_pk_bf16_f32 v89, v178, v179
	s_nop 1
	v_mfma_f32_16x16x32_bf16 v[30:33], v[220:223], v[82:85], v[30:33]
	v_mfma_f32_16x16x32_bf16 v[26:29], v[228:231], v[82:85], v[26:29]
	v_mfma_f32_16x16x32_bf16 v[22:25], v[236:239], v[82:85], v[22:25]
	v_mfma_f32_16x16x32_bf16 v[18:21], v[244:247], v[82:85], v[18:21]
	v_mfma_f32_16x16x32_bf16 v[30:33], v[224:227], v[86:89], v[30:33]
	v_mfma_f32_16x16x32_bf16 v[26:29], v[232:235], v[86:89], v[26:29]
	v_mfma_f32_16x16x32_bf16 v[22:25], v[240:243], v[86:89], v[22:25]
	v_mfma_f32_16x16x32_bf16 v[18:21], v[198:201], v[86:89], v[18:21]
	v_mfma_f32_16x16x32_bf16 v[46:49], v[90:93], v[82:85], v[46:49]
	v_mfma_f32_16x16x32_bf16 v[46:49], v[90:93], v[86:89], v[46:49]
	s_branch .LBB0_667_p1

; template <bool FX>
; DI void nsa_tile(const Params& p, int b, int g, int tile, bf16_t* lds, const float CL) {
;     ...
;       for (int s = 0; s <= cur; ++s) {
;         __syncthreads();
;         tile64_sstore(tid, Ks, rk0, rk1);
;         tile64_sstore(tid, Vs, rv0, rv1);
;         __syncthreads();
;         if (s < cur) {
;           tile64_gload(tid, rk0, rk1, kb + (size_t)(s + 1) * 64 * ZS, ZS);
;           tile64_gload(tid, rv0, rv1, vsT + (s + 1) * 64, TS);
;         }
;         uint32_t wsel = (s < 32) ? sw0 : (s < 64) ? sw1 : (s < 96) ? sw2 : sw3;
;         bool sel = (wsel >> (s & 31)) & 1u;
;         int hi = sel ? (tok - s * 64) : -1;
;         if (__any(hi >= 0)) attn_compute<2, FX>(lane, Ks, Vs, qf, st, invl, 0, hi, dA, dE, CL);
.LBB0_667_p1:
	s_add_i32 s28, s28, 64
	v_lshl_add_u64 v[160:161], v[160:161], 0, s[22:23]
	v_lshl_add_u64 v[158:159], v[158:159], 0, s[22:23]
	s_cmp_eq_u32 s25, s68
	v_subrev_u32_e32 v187, 64, v187
	s_cbranch_scc1 .LBB0_675
	s_branch .LBB0_668

; DI f32x4 mfma16(bf16x8 a, bf16x8 b, f32x4 c) { return __builtin_amdgcn_mfma_f32_16x16x32_bf16(a, b, c, 0, 0, 0); }
; template <int MODE, bool FX>
; DI void attn_compute(const int lane, const bf16_t* Ks, const bf16_t* Vs, const bf16x8 (&qf)[2][2], AttnSt& st, const float (&invl)[2],
;                      int lo, int hi, float (&impA)[4], float (&impE)[4], const float CL) {
;     ...
;   for (int ks = 0; ks < 2; ++ks) {
; #pragma unroll
;     for (int kt = 0; kt < 4; ++kt) {
;       int row = kt * 16 + col;
;       bf16x8 kf = *(const bf16x8*)(Ks + row * 64 + (((ks * 4 + quad) ^ ((row >> 1) & 7)) << 3));
; #pragma unroll
;       for (int hh = 0; hh < 2; ++hh) S[kt][hh] = mfma16(kf, qf[hh][ks], S[kt][hh]);
;     }
;   }
;     ...
; #pragma unroll
;   for (int hh = 0; hh < 2; ++hh) {
;     if (FX) {
;       constexpr float L2E = 1.4426950408889634f;
;       const float il = (MODE == 1) ? invl[hh] : 1.f;
;       float rs = 0.f;
; #pragma unroll
;       for (int kt = 0; kt < 4; ++kt) {
;         float a = 0.f;
; #pragma unroll
;         for (int j = 0; j < 4; ++j) {
;           const int kl = kt * 16 + quad * 4 + j;
;           const bool v = (kl >= lo) && (kl <= hi);
;           float pv = v ? __builtin_amdgcn_exp2f(fmaf(S[kt][hh][j], L2E, -CL)) : 0.f;
;           if (MODE == 1) pv *= il;
;           S[kt][hh][j] = pv;
;           a += pv;
;         }
;         rs += a;
;         if (MODE == 1) {
;           impA[kt] += a;
;           impE[kt] += S[kt][hh][3];
;         }
;       }
;       if (MODE != 1 && !(FX && MODE == 2)) st.l[hh] += rs;
;       if (MODE != 0) {
; #pragma unroll
;         for (int c = 0; c < 2; ++c)
;           pf[hh][c] = mk8(pack2(S[2 * c][hh][0], S[2 * c][hh][1]), pack2(S[2 * c][hh][2], S[2 * c][hh][3]),
;                           pack2(S[2 * c + 1][hh][0], S[2 * c + 1][hh][1]), pack2(S[2 * c + 1][hh][2], S[2 * c + 1][hh][3]));
;       }
.LBB0_670_p1:
	s_cbranch_vccz .LBB0_667_p1
	ds_read_b128 v[220:223], v188 offset:49152
	ds_read_b128 v[224:227], v188 offset:51200
	ds_read_b128 v[228:231], v188 offset:53248
	ds_read_b128 v[232:235], v189 offset:49152
	ds_read_b128 v[236:239], v190 offset:49152
	ds_read_b128 v[240:243], v190 offset:51200
	ds_read_b128 v[244:247], v190 offset:53248
	ds_read_b128 v[198:201], v191 offset:49152
	v_cmp_lt_u32_e32 vcc, 62, v215
	s_mov_b64 s[2:3], -1
	s_cmp_eq_u64 vcc, exec
	s_cbranch_scc1 .Lnsa_fast_p1
	s_waitcnt lgkmcnt(7)
	v_mfma_f32_16x16x32_bf16 v[98:101], v[220:223], v[2:5], 0
	v_mfma_f32_16x16x32_bf16 v[90:93], v[220:223], v[10:13], 0
	s_waitcnt lgkmcnt(6)
	v_mfma_f32_16x16x32_bf16 v[106:109], v[224:227], v[2:5], 0
	v_mfma_f32_16x16x32_bf16 v[94:97], v[224:227], v[10:13], 0
	s_waitcnt lgkmcnt(5)
	v_mfma_f32_16x16x32_bf16 v[102:105], v[228:231], v[2:5], 0
	v_mfma_f32_16x16x32_bf16 v[82:85], v[228:231], v[10:13], 0
	s_waitcnt lgkmcnt(4)
	v_mfma_f32_16x16x32_bf16 v[110:113], v[232:235], v[2:5], 0
	v_mfma_f32_16x16x32_bf16 v[86:89], v[232:235], v[10:13], 0
	s_waitcnt lgkmcnt(3)
	v_mfma_f32_16x16x32_bf16 v[98:101], v[236:239], v[6:9], v[98:101]
	v_mfma_f32_16x16x32_bf16 v[90:93], v[236:239], v[14:17], v[90:93]
	s_waitcnt lgkmcnt(2)
	v_mfma_f32_16x16x32_bf16 v[106:109], v[240:243], v[6:9], v[106:109]
	v_mfma_f32_16x16x32_bf16 v[94:97], v[240:243], v[14:17], v[94:97]
	s_waitcnt lgkmcnt(1)
	v_mfma_f32_16x16x32_bf16 v[102:105], v[244:247], v[6:9], v[102:105]
	v_mfma_f32_16x16x32_bf16 v[82:85], v[244:247], v[14:17], v[82:85]
	s_waitcnt lgkmcnt(0)
	v_mfma_f32_16x16x32_bf16 v[110:113], v[198:201], v[6:9], v[110:113]
	v_mfma_f32_16x16x32_bf16 v[86:89], v[198:201], v[14:17], v[86:89]
	ds_read_b64 v[220:221], v207 offset:57344
	ds_read_b64 v[222:223], v208 offset:57344
	ds_read_b64 v[224:225], v209 offset:57344
	ds_read_b64 v[226:227], v210 offset:57344
	ds_read_b64 v[228:229], v207 offset:59392
	ds_read_b64 v[230:231], v208 offset:59392
	ds_read_b64 v[232:233], v209 offset:59392
	ds_read_b64 v[234:235], v210 offset:59392
	ds_read_b64 v[236:237], v207 offset:61440
	ds_read_b64 v[238:239], v208 offset:61440
	ds_read_b64 v[240:241], v209 offset:61440
	ds_read_b64 v[242:243], v210 offset:61440
	ds_read_b64 v[244:245], v211 offset:57344
	ds_read_b64 v[246:247], v212 offset:57344
	ds_read_b64 v[198:199], v213 offset:57344
	ds_read_b64 v[200:201], v214 offset:57344
	s_cbranch_scc1 .LBB0_673_p1
	v_fmamk_f32 v74, v98, 0x3fb8aa3b, v205
	v_fmamk_f32 v75, v99, 0x3fb8aa3b, v205
	v_fmamk_f32 v76, v100, 0x3fb8aa3b, v205
	v_fmamk_f32 v77, v101, 0x3fb8aa3b, v205
	v_fmamk_f32 v78, v106, 0x3fb8aa3b, v205
	v_fmamk_f32 v79, v107, 0x3fb8aa3b, v205
	v_fmamk_f32 v80, v108, 0x3fb8aa3b, v205
	v_fmamk_f32 v81, v109, 0x3fb8aa3b, v205
	v_fmamk_f32 v164, v102, 0x3fb8aa3b, v205
	v_fmamk_f32 v165, v103, 0x3fb8aa3b, v205
	v_fmamk_f32 v166, v104, 0x3fb8aa3b, v205
	v_fmamk_f32 v167, v105, 0x3fb8aa3b, v205
	v_fmamk_f32 v168, v110, 0x3fb8aa3b, v205
	v_fmamk_f32 v169, v111, 0x3fb8aa3b, v205
	v_fmamk_f32 v170, v112, 0x3fb8aa3b, v205
	v_fmamk_f32 v171, v113, 0x3fb8aa3b, v205
	v_exp_f32_e32 v74, v74
	v_exp_f32_e32 v75, v75
	v_exp_f32_e32 v76, v76
	v_exp_f32_e32 v77, v77
	v_exp_f32_e32 v78, v78
	v_exp_f32_e32 v79, v79
	v_exp_f32_e32 v80, v80
	v_exp_f32_e32 v81, v81
	v_exp_f32_e32 v164, v164
	v_exp_f32_e32 v165, v165
	v_exp_f32_e32 v166, v166
	v_exp_f32_e32 v167, v167
	v_exp_f32_e32 v168, v168
	v_exp_f32_e32 v169, v169
	v_exp_f32_e32 v170, v170
	v_exp_f32_e32 v171, v171
	v_cmp_gt_i32_e32 vcc, v118, v215
	v_cmp_lt_i32_e64 s[2:3], v118, v215
	v_cmp_gt_i32_e64 s[52:53], v119, v215
	v_cmp_gt_i32_e64 s[54:55], v192, v215
	v_cmp_gt_i32_e64 s[40:41], v120, v215
	v_cmp_gt_i32_e64 s[42:43], v193, v215
	v_cmp_gt_i32_e64 s[56:57], v122, v215
	v_cmp_gt_i32_e64 s[58:59], v121, v215
	v_cmp_gt_i32_e64 s[44:45], v194, v215
	v_cmp_gt_i32_e64 s[46:47], v195, v215
	v_cmp_gt_i32_e64 s[60:61], v206, v215
	v_cmp_gt_i32_e64 s[62:63], v124, v215
	v_cmp_gt_i32_e64 s[48:49], v126, v215
	v_cmp_gt_i32_e64 s[50:51], v123, v215
	v_cmp_gt_i32_e64 s[64:65], v125, v215
	v_cmp_gt_i32_e64 s[66:67], v127, v215
	v_cndmask_b32_e64 v74, v74, 0, vcc
	v_cndmask_b32_e64 v75, 0, v75, s[2:3]
	v_cndmask_b32_e64 v76, v76, 0, s[52:53]
	v_cndmask_b32_e64 v77, v77, 0, s[54:55]
	v_cndmask_b32_e64 v78, v78, 0, s[40:41]
	v_cndmask_b32_e64 v79, v79, 0, s[42:43]
	v_cndmask_b32_e64 v80, v80, 0, s[56:57]
	v_cndmask_b32_e64 v81, v81, 0, s[58:59]
	v_cndmask_b32_e64 v164, v164, 0, s[44:45]
	v_cndmask_b32_e64 v165, v165, 0, s[46:47]
	v_cndmask_b32_e64 v166, v166, 0, s[60:61]
	v_cndmask_b32_e64 v167, v167, 0, s[62:63]
	v_cndmask_b32_e64 v168, v168, 0, s[48:49]
	v_cndmask_b32_e64 v169, v169, 0, s[50:51]
	v_cndmask_b32_e64 v170, v170, 0, s[64:65]
	v_cndmask_b32_e64 v171, v171, 0, s[66:67]
	v_cvt_pk_bf16_f32 v74, v74, v75
	v_cvt_pk_bf16_f32 v75, v76, v77
	v_cvt_pk_bf16_f32 v76, v78, v79
	v_cvt_pk_bf16_f32 v77, v80, v81
	v_cvt_pk_bf16_f32 v78, v164, v165
	v_cvt_pk_bf16_f32 v79, v166, v167
	v_cvt_pk_bf16_f32 v80, v168, v169
	v_cvt_pk_bf16_f32 v81, v170, v171
	v_fmamk_f32 v164, v90, 0x3fb8aa3b, v205
	v_fmamk_f32 v165, v91, 0x3fb8aa3b, v205
	v_fmamk_f32 v166, v92, 0x3fb8aa3b, v205
	v_fmamk_f32 v167, v93, 0x3fb8aa3b, v205
	v_fmamk_f32 v168, v94, 0x3fb8aa3b, v205
	v_fmamk_f32 v169, v95, 0x3fb8aa3b, v205
	v_fmamk_f32 v170, v96, 0x3fb8aa3b, v205
	v_fmamk_f32 v171, v97, 0x3fb8aa3b, v205
	v_fmamk_f32 v172, v82, 0x3fb8aa3b, v205
	v_fmamk_f32 v173, v83, 0x3fb8aa3b, v205
	v_fmamk_f32 v174, v84, 0x3fb8aa3b, v205
	v_fmamk_f32 v175, v85, 0x3fb8aa3b, v205
	v_fmamk_f32 v176, v86, 0x3fb8aa3b, v205
	v_fmamk_f32 v177, v87, 0x3fb8aa3b, v205
	v_fmamk_f32 v178, v88, 0x3fb8aa3b, v205
	v_fmamk_f32 v179, v89, 0x3fb8aa3b, v205
	v_exp_f32_e32 v164, v164
	v_exp_f32_e32 v165, v165
	v_exp_f32_e32 v166, v166
	v_exp_f32_e32 v167, v167
	v_exp_f32_e32 v168, v168
	v_exp_f32_e32 v169, v169
	v_exp_f32_e32 v170, v170
	v_exp_f32_e32 v171, v171
	v_exp_f32_e32 v172, v172
	v_exp_f32_e32 v173, v173
	v_exp_f32_e32 v174, v174
	v_exp_f32_e32 v175, v175
	v_exp_f32_e32 v176, v176
	v_exp_f32_e32 v177, v177
	v_exp_f32_e32 v178, v178
	v_exp_f32_e32 v179, v179
	v_cndmask_b32_e64 v164, v164, 0, vcc
	v_cndmask_b32_e64 v165, 0, v165, s[2:3]
	v_cndmask_b32_e64 v166, v166, 0, s[52:53]
	v_cndmask_b32_e64 v167, v167, 0, s[54:55]
	v_cndmask_b32_e64 v168, v168, 0, s[40:41]
	v_cndmask_b32_e64 v169, v169, 0, s[42:43]
	v_cndmask_b32_e64 v170, v170, 0, s[56:57]
	v_cndmask_b32_e64 v171, v171, 0, s[58:59]
	v_cndmask_b32_e64 v172, v172, 0, s[44:45]
	v_cndmask_b32_e64 v173, v173, 0, s[46:47]
	v_cndmask_b32_e64 v174, v174, 0, s[60:61]
	v_cndmask_b32_e64 v175, v175, 0, s[62:63]
	v_cndmask_b32_e64 v176, v176, 0, s[48:49]
	v_cndmask_b32_e64 v177, v177, 0, s[50:51]
	v_cndmask_b32_e64 v178, v178, 0, s[64:65]
	v_cndmask_b32_e64 v179, v179, 0, s[66:67]
	s_mov_b64 s[2:3], 0
; template <int MODE, bool FX>
; DI void attn_compute(const int lane, const bf16_t* Ks, const bf16_t* Vs, const bf16x8 (&qf)[2][2], AttnSt& st, const float (&invl)[2],
;                      int lo, int hi, float (&impA)[4], float (&impE)[4], const float CL) {
;     ...
;   if (__all(full || none)) {
;     constexpr float L2E = 1.4426950408889634f;
; #pragma unroll
;     for (int hh = 0; hh < 2; ++hh) {
;       float mL;
;       float il = 1.f;
;       if (FX) {
;         mL = full ? CL : 1e30f;
;         if (MODE == 1) il = invl[hh];
;       } else if (MODE != 1) {
;         float mx = -1e30f;
; #pragma unroll
;         for (int kt = 0; kt < 4; ++kt)
; #pragma unroll
;           for (int j = 0; j < 4; ++j) mx = fmaxf(mx, S[kt][hh][j]);
;         mx = full ? mx : -1e30f;
;         mx = fmaxf(mx, shx(mx, 16, lane));
;         mx = fmaxf(mx, shx(mx, 32, lane));
;         const float m_new = fmaxf(st.m[hh], mx);
;         const float alpha = __expf(st.m[hh] - m_new);
;         st.m[hh] = m_new;
;         st.l[hh] *= alpha;
;         if (MODE == 2) {
; #pragma unroll
;           for (int dt = 0; dt < 4; ++dt) st.O[hh][dt] *= alpha;
;         }
;         mL = full ? m_new * L2E : 1e30f;
;       } else {
;         mL = full ? st.m[hh] * L2E : 1e30f;
;         il = invl[hh];
;       }
;       float rs = 0.f;
; #pragma unroll
;       for (int kt = 0; kt < 4; ++kt) {
;         float a = 0.f;
; #pragma unroll
;         for (int j = 0; j < 4; ++j) {
;           float pv = __builtin_amdgcn_exp2f(fmaf(S[kt][hh][j], L2E, -mL));
;           if (MODE == 1) pv *= il;
;           S[kt][hh][j] = pv;
;           a += pv;
;         }
;         rs += a;
;         if (MODE == 1) {
;           impA[kt] += a;
;           impE[kt] += S[kt][hh][3];
;         }
;       }
;       if (MODE != 1 && !(FX && MODE == 2)) st.l[hh] += rs;
;       if (MODE != 0) {
; #pragma unroll
;         for (int c = 0; c < 2; ++c)
;           pf[hh][c] = mk8(pack2(S[2 * c][hh][0], S[2 * c][hh][1]), pack2(S[2 * c][hh][2], S[2 * c][hh][3]),
;                           pack2(S[2 * c + 1][hh][0], S[2 * c + 1][hh][1]), pack2(S[2 * c + 1][hh][2], S[2 * c + 1][hh][3]));
;       }
;     }
.LBB0_673_p1:
	s_andn2_b64 vcc, exec, s[2:3]
	s_cbranch_vccnz .LBB0_666_p1
	v_cmp_lt_i32_e32 vcc, 62, v215
	s_nop 1
	v_cndmask_b32_e32 v79, v197, v205, vcc
	v_fmamk_f32 v74, v98, 0x3fb8aa3b, v79
	v_fmamk_f32 v75, v99, 0x3fb8aa3b, v79
	v_fmamk_f32 v76, v100, 0x3fb8aa3b, v79
	v_fmamk_f32 v77, v101, 0x3fb8aa3b, v79
	v_fmamk_f32 v78, v106, 0x3fb8aa3b, v79
	v_fmamk_f32 v80, v107, 0x3fb8aa3b, v79
	v_exp_f32_e32 v74, v74
	v_exp_f32_e32 v75, v75
	v_exp_f32_e32 v76, v76
	v_exp_f32_e32 v77, v77
	v_exp_f32_e32 v78, v78
	v_exp_f32_e32 v80, v80
	v_cvt_pk_bf16_f32 v74, v74, v75
	v_cvt_pk_bf16_f32 v75, v76, v77
	v_fmamk_f32 v81, v108, 0x3fb8aa3b, v79
	v_cvt_pk_bf16_f32 v76, v78, v80
	v_fmamk_f32 v80, v90, 0x3fb8aa3b, v79
	v_exp_f32_e32 v164, v80
	v_fmamk_f32 v80, v91, 0x3fb8aa3b, v79
	v_exp_f32_e32 v165, v80
	v_fmamk_f32 v80, v92, 0x3fb8aa3b, v79
	v_exp_f32_e32 v166, v80
	v_fmamk_f32 v80, v93, 0x3fb8aa3b, v79
	v_exp_f32_e32 v167, v80
	v_fmamk_f32 v80, v94, 0x3fb8aa3b, v79
	v_exp_f32_e32 v168, v80
	v_fmamk_f32 v80, v95, 0x3fb8aa3b, v79
	v_exp_f32_e32 v169, v80
	v_fmamk_f32 v80, v96, 0x3fb8aa3b, v79
	v_exp_f32_e32 v170, v80
	v_fmamk_f32 v80, v97, 0x3fb8aa3b, v79
	v_exp_f32_e32 v171, v80
	v_fmamk_f32 v80, v82, 0x3fb8aa3b, v79
	v_exp_f32_e32 v172, v80
	v_fmamk_f32 v80, v83, 0x3fb8aa3b, v79
	v_exp_f32_e32 v173, v80
	v_fmamk_f32 v80, v84, 0x3fb8aa3b, v79
	v_exp_f32_e32 v174, v80
	v_fmamk_f32 v80, v85, 0x3fb8aa3b, v79
	v_exp_f32_e32 v175, v80
	v_fmamk_f32 v80, v86, 0x3fb8aa3b, v79
	v_fmamk_f32 v98, v109, 0x3fb8aa3b, v79
	v_fmamk_f32 v99, v102, 0x3fb8aa3b, v79
	v_fmamk_f32 v100, v103, 0x3fb8aa3b, v79
	v_fmamk_f32 v101, v104, 0x3fb8aa3b, v79
	v_fmamk_f32 v102, v105, 0x3fb8aa3b, v79
	v_fmamk_f32 v103, v110, 0x3fb8aa3b, v79
	v_fmamk_f32 v104, v111, 0x3fb8aa3b, v79
	v_fmamk_f32 v105, v112, 0x3fb8aa3b, v79
	v_fmamk_f32 v106, v113, 0x3fb8aa3b, v79
	v_exp_f32_e32 v176, v80
	v_fmamk_f32 v80, v87, 0x3fb8aa3b, v79
	v_exp_f32_e32 v81, v81
	v_exp_f32_e32 v98, v98
	v_exp_f32_e32 v99, v99
	v_exp_f32_e32 v100, v100
	v_exp_f32_e32 v101, v101
	v_exp_f32_e32 v102, v102
	v_exp_f32_e32 v103, v103
	v_exp_f32_e32 v104, v104
	v_exp_f32_e32 v105, v105
	v_exp_f32_e32 v106, v106
	v_exp_f32_e32 v177, v80
	v_fmamk_f32 v80, v88, 0x3fb8aa3b, v79
	v_fmac_f32_e32 v79, 0x3fb8aa3b, v89
	v_exp_f32_e32 v178, v80
	v_exp_f32_e32 v179, v79
	v_cvt_pk_bf16_f32 v77, v81, v98
	v_cvt_pk_bf16_f32 v78, v99, v100
	v_cvt_pk_bf16_f32 v79, v101, v102
	v_cvt_pk_bf16_f32 v80, v103, v104
	v_cvt_pk_bf16_f32 v81, v105, v106
	s_branch .LBB0_666_p1
; template <int MODE, bool FX>
; DI void attn_compute(const int lane, const bf16_t* Ks, const bf16_t* Vs, const bf16x8 (&qf)[2][2], AttnSt& st, const float (&invl)[2],
;                      int lo, int hi, float (&impA)[4], float (&impE)[4], const float CL) {
;     ...
;   if (__all(full || none)) {
;     constexpr float L2E = 1.4426950408889634f;
; #pragma unroll
;     for (int hh = 0; hh < 2; ++hh) {
;       float mL;
;       float il = 1.f;
;       if (FX) {
;         mL = full ? CL : 1e30f;
;         if (MODE == 1) il = invl[hh];
;       } else if (MODE != 1) {
;         float mx = -1e30f;
; #pragma unroll
;         for (int kt = 0; kt < 4; ++kt)
; #pragma unroll
;           for (int j = 0; j < 4; ++j) mx = fmaxf(mx, S[kt][hh][j]);
;         mx = full ? mx : -1e30f;
;         mx = fmaxf(mx, shx(mx, 16, lane));
;         mx = fmaxf(mx, shx(mx, 32, lane));
;         const float m_new = fmaxf(st.m[hh], mx);
;         const float alpha = __expf(st.m[hh] - m_new);
;         st.m[hh] = m_new;
;         st.l[hh] *= alpha;
;         if (MODE == 2) {
; #pragma unroll
;           for (int dt = 0; dt < 4; ++dt) st.O[hh][dt] *= alpha;
;         }
;         mL = full ? m_new * L2E : 1e30f;
;       } else {
;         mL = full ? st.m[hh] * L2E : 1e30f;
;         il = invl[hh];
;       }
;       float rs = 0.f;
; #pragma unroll
;       for (int kt = 0; kt < 4; ++kt) {
;         float a = 0.f;
; #pragma unroll
;         for (int j = 0; j < 4; ++j) {
;           float pv = __builtin_amdgcn_exp2f(fmaf(S[kt][hh][j], L2E, -mL));
;           if (MODE == 1) pv *= il;
;           S[kt][hh][j] = pv;
;           a += pv;
;         }
;         rs += a;
;         if (MODE == 1) {
;           impA[kt] += a;
;           impE[kt] += S[kt][hh][3];
;         }
;       }
;       if (MODE != 1 && !(FX && MODE == 2)) st.l[hh] += rs;
;       if (MODE != 0) {
; #pragma unroll
;         for (int c = 0; c < 2; ++c)
;           pf[hh][c] = mk8(pack2(S[2 * c][hh][0], S[2 * c][hh][1]), pack2(S[2 * c][hh][2], S[2 * c][hh][3]),
;                           pack2(S[2 * c + 1][hh][0], S[2 * c + 1][hh][1]), pack2(S[2 * c + 1][hh][2], S[2 * c + 1][hh][3]));
;       }
;     }
;     ...
;   if (MODE != 0) {
; #pragma unroll
;     for (int dt = 0; dt < 4; ++dt) {
;       const int row = dt * 16 + col;
;       const int sw = (row >> 1) & 7;
; #pragma unroll
;       for (int c = 0; c < 2; ++c) {
.Lnsa_fast:
	s_waitcnt lgkmcnt(7)
	v_mfma_f32_16x16x32_bf16 v[98:101], v[220:223], v[2:5], 0
	s_waitcnt lgkmcnt(6)
	v_mfma_f32_16x16x32_bf16 v[106:109], v[224:227], v[2:5], 0
	s_waitcnt lgkmcnt(5)
	v_mfma_f32_16x16x32_bf16 v[102:105], v[228:231], v[2:5], 0
	s_waitcnt lgkmcnt(4)
	v_mfma_f32_16x16x32_bf16 v[110:113], v[232:235], v[2:5], 0
	s_waitcnt lgkmcnt(3)
	v_mfma_f32_16x16x32_bf16 v[98:101], v[236:239], v[6:9], v[98:101]
	s_waitcnt lgkmcnt(2)
	v_mfma_f32_16x16x32_bf16 v[106:109], v[240:243], v[6:9], v[106:109]
	s_waitcnt lgkmcnt(1)
	v_mfma_f32_16x16x32_bf16 v[102:105], v[244:247], v[6:9], v[102:105]
	s_waitcnt lgkmcnt(0)
	v_mfma_f32_16x16x32_bf16 v[110:113], v[198:201], v[6:9], v[110:113]
	v_cmp_lt_i32_e32 vcc, 62, v215
	v_mfma_f32_16x16x32_bf16 v[90:93], v[220:223], v[10:13], 0
	v_mfma_f32_16x16x32_bf16 v[94:97], v[224:227], v[10:13], 0
	v_cndmask_b32_e32 v217, v197, v205, vcc
	v_mfma_f32_16x16x32_bf16 v[82:85], v[228:231], v[10:13], 0
	v_mfma_f32_16x16x32_bf16 v[86:89], v[232:235], v[10:13], 0
	v_fmamk_f32 v74, v98, 0x3fb8aa3b, v217
	v_fmamk_f32 v75, v99, 0x3fb8aa3b, v217
	v_mfma_f32_16x16x32_bf16 v[90:93], v[236:239], v[14:17], v[90:93]
	v_fmamk_f32 v76, v100, 0x3fb8aa3b, v217
	v_fmamk_f32 v77, v101, 0x3fb8aa3b, v217
	v_mfma_f32_16x16x32_bf16 v[94:97], v[240:243], v[14:17], v[94:97]
	v_fmamk_f32 v78, v106, 0x3fb8aa3b, v217
	v_fmamk_f32 v79, v107, 0x3fb8aa3b, v217
	v_mfma_f32_16x16x32_bf16 v[82:85], v[244:247], v[14:17], v[82:85]
	v_fmamk_f32 v80, v108, 0x3fb8aa3b, v217
	v_fmamk_f32 v81, v109, 0x3fb8aa3b, v217
	v_mfma_f32_16x16x32_bf16 v[86:89], v[198:201], v[14:17], v[86:89]
	ds_read_b64 v[220:221], v207 offset:8192
	v_fmamk_f32 v164, v102, 0x3fb8aa3b, v217
	ds_read_b64 v[222:223], v208 offset:8192
	v_fmamk_f32 v165, v103, 0x3fb8aa3b, v217
	ds_read_b64 v[224:225], v209 offset:8192
	v_fmamk_f32 v166, v104, 0x3fb8aa3b, v217
	ds_read_b64 v[226:227], v210 offset:8192
	v_fmamk_f32 v167, v105, 0x3fb8aa3b, v217
	ds_read_b64 v[228:229], v207 offset:10240
	v_fmamk_f32 v168, v110, 0x3fb8aa3b, v217
	ds_read_b64 v[230:231], v208 offset:10240
	v_fmamk_f32 v169, v111, 0x3fb8aa3b, v217
	ds_read_b64 v[232:233], v209 offset:10240
	v_fmamk_f32 v170, v112, 0x3fb8aa3b, v217
	ds_read_b64 v[234:235], v210 offset:10240
	v_fmamk_f32 v171, v113, 0x3fb8aa3b, v217
	ds_read_b64 v[236:237], v207 offset:12288
	v_exp_f32_e32 v74, v74
	ds_read_b64 v[238:239], v208 offset:12288
	v_exp_f32_e32 v75, v75
	ds_read_b64 v[240:241], v209 offset:12288
	v_exp_f32_e32 v76, v76
	ds_read_b64 v[242:243], v210 offset:12288
	v_exp_f32_e32 v77, v77
	ds_read_b64 v[244:245], v211 offset:8192
	v_exp_f32_e32 v78, v78
	ds_read_b64 v[246:247], v212 offset:8192
	v_exp_f32_e32 v79, v79
	ds_read_b64 v[198:199], v213 offset:8192
	v_exp_f32_e32 v80, v80
	ds_read_b64 v[200:201], v214 offset:8192
	v_exp_f32_e32 v81, v81
	v_exp_f32_e32 v164, v164
	v_exp_f32_e32 v165, v165
	v_exp_f32_e32 v166, v166
	v_exp_f32_e32 v167, v167
	v_exp_f32_e32 v168, v168
	v_exp_f32_e32 v169, v169
	v_exp_f32_e32 v170, v170
	v_exp_f32_e32 v171, v171
	v_cvt_pk_bf16_f32 v74, v74, v75
	v_cvt_pk_bf16_f32 v75, v76, v77
	v_cvt_pk_bf16_f32 v76, v78, v79
	v_cvt_pk_bf16_f32 v77, v80, v81
	v_cvt_pk_bf16_f32 v78, v164, v165
	v_cvt_pk_bf16_f32 v79, v166, v167
	v_cvt_pk_bf16_f32 v80, v168, v169
	v_cvt_pk_bf16_f32 v81, v170, v171
	s_waitcnt lgkmcnt(0)
	v_fmamk_f32 v164, v90, 0x3fb8aa3b, v217
	v_fmamk_f32 v165, v91, 0x3fb8aa3b, v217
	v_fmamk_f32 v166, v92, 0x3fb8aa3b, v217
	v_mfma_f32_16x16x32_bf16 v[50:53], v[220:223], v[74:77], v[50:53]
	v_fmamk_f32 v167, v93, 0x3fb8aa3b, v217
	s_mov_b32 s10, s8
	s_mov_b32 s11, s8
	s_mov_b32 s9, s8
	v_mfma_f32_16x16x32_bf16 v[42:45], v[228:231], v[74:77], v[42:45]
	v_mov_b64_e32 v[92:93], s[10:11]
	v_mov_b64_e32 v[90:91], s[8:9]
	v_fmamk_f32 v168, v94, 0x3fb8aa3b, v217
	v_fmamk_f32 v169, v95, 0x3fb8aa3b, v217
	v_mfma_f32_16x16x32_bf16 v[38:41], v[236:239], v[74:77], v[38:41]
	v_fmamk_f32 v170, v96, 0x3fb8aa3b, v217
	v_fmamk_f32 v171, v97, 0x3fb8aa3b, v217
	v_fmamk_f32 v172, v82, 0x3fb8aa3b, v217
	v_fmamk_f32 v173, v83, 0x3fb8aa3b, v217
	v_mfma_f32_16x16x32_bf16 v[34:37], v[244:247], v[74:77], v[34:37]
	v_fmamk_f32 v174, v84, 0x3fb8aa3b, v217
	v_fmamk_f32 v175, v85, 0x3fb8aa3b, v217
	v_fmamk_f32 v176, v86, 0x3fb8aa3b, v217
	v_fmamk_f32 v177, v87, 0x3fb8aa3b, v217
	v_mfma_f32_16x16x32_bf16 v[50:53], v[224:227], v[78:81], v[50:53]
	v_fmamk_f32 v178, v88, 0x3fb8aa3b, v217
	v_fmamk_f32 v179, v89, 0x3fb8aa3b, v217
	v_exp_f32_e32 v164, v164
	v_exp_f32_e32 v165, v165
	v_mfma_f32_16x16x32_bf16 v[42:45], v[232:235], v[78:81], v[42:45]
	v_exp_f32_e32 v166, v166
	v_exp_f32_e32 v167, v167
	v_exp_f32_e32 v168, v168
	v_exp_f32_e32 v169, v169
	v_mfma_f32_16x16x32_bf16 v[38:41], v[240:243], v[78:81], v[38:41]
	v_exp_f32_e32 v170, v170
	v_exp_f32_e32 v171, v171
	v_exp_f32_e32 v172, v172
	v_exp_f32_e32 v173, v173
	v_mfma_f32_16x16x32_bf16 v[34:37], v[198:201], v[78:81], v[34:37]
	v_exp_f32_e32 v174, v174
	v_exp_f32_e32 v175, v175
	v_exp_f32_e32 v176, v176
	v_exp_f32_e32 v177, v177
	v_mfma_f32_16x16x32_bf16 v[54:57], v[90:93], v[74:77], v[54:57]
	v_exp_f32_e32 v178, v178
	v_exp_f32_e32 v179, v179
	v_cvt_pk_bf16_f32 v82, v164, v165
	v_cvt_pk_bf16_f32 v83, v166, v167
	v_mfma_f32_16x16x32_bf16 v[54:57], v[90:93], v[78:81], v[54:57]
	v_cvt_pk_bf16_f32 v84, v168, v169
	v_cvt_pk_bf16_f32 v85, v170, v171
	v_cvt_pk_bf16_f32 v86, v172, v173
	v_cvt_pk_bf16_f32 v87, v174, v175
	v_cvt_pk_bf16_f32 v88, v176, v177
	v_cvt_pk_bf16_f32 v89, v178, v179
	s_nop 1
	v_mfma_f32_16x16x32_bf16 v[30:33], v[220:223], v[82:85], v[30:33]
	v_mfma_f32_16x16x32_bf16 v[26:29], v[228:231], v[82:85], v[26:29]
	v_mfma_f32_16x16x32_bf16 v[22:25], v[236:239], v[82:85], v[22:25]
	v_mfma_f32_16x16x32_bf16 v[18:21], v[244:247], v[82:85], v[18:21]
	v_mfma_f32_16x16x32_bf16 v[30:33], v[224:227], v[86:89], v[30:33]
	v_mfma_f32_16x16x32_bf16 v[26:29], v[232:235], v[86:89], v[26:29]
	v_mfma_f32_16x16x32_bf16 v[22:25], v[240:243], v[86:89], v[22:25]
	v_mfma_f32_16x16x32_bf16 v[18:21], v[198:201], v[86:89], v[18:21]
	v_mfma_f32_16x16x32_bf16 v[46:49], v[90:93], v[82:85], v[46:49]
	v_mfma_f32_16x16x32_bf16 v[46:49], v[90:93], v[86:89], v[46:49]
	s_branch .LBB0_667
